# P0 rewritten: k-fastest unit order + nt streaming loads; attention pass 0: K/V half-window kept in registers, epilogue stores widened to dwordx4 via permlane16_swap
# speedup vs baseline: 1.0099x; 1.0099x over previous
; __global__ void __launch_bounds__(512, 2) fwd_megakernel(Args a) {
;     ...
;         for (int it = gw; it < I1 + I2 + I3 + I4 + I5; it += NGW) {
;             int r = it;
;             if (r < I1) { const int kb = r / 320, nb = r % 320; transpose_item(w_in_ab, 10240, 64 * kb, 32 * nb, WT1, 2048, 32 * nb, scr, lane); continue; } r -= I1;
;             if (r < I2) { const int kb = r / 64, nb = r % 64; transpose_item(w_out_ab, 2048, 64 * kb, 32 * nb, WT2, 3072, 32 * nb, scr, lane); continue; } r -= I2;
;             if (r < I3) { const int kb = r / 256, nb = r % 256; const int n0 = 32 * nb, part = n0 >> 11, chn = n0 & 2047;
;                 const int type = (part == 0 || part == 3) ? 1 : 0, bj = (part >= 2) ? 1 : 0;
;                 const int drow = 256 * (2 * (chn >> 7) + type) + 128 * bj + (chn & 127);
;                 transpose_item(w_in_c, 8192, 64 * kb, n0, WT3, 2048, drow, scr, lane); continue; } r -= I3;
;             if (r < I4) { const int kb = r / 64, nb = r % 64; transpose_item(w_out_c, 2048, 64 * kb, 32 * nb, WT4, 2048, 32 * nb, scr, lane); continue; } r -= I4;
;             { const int gi = r >> 5, rr = r & 31, kb = rr >> 3, nb = rr & 7; transpose_item(pool_w + (size_t)gi * 65536, 256, 64 * kb, 32 * nb, WT5, 256, gi * 256 + 32 * nb, scr, lane); }
.LBB0_3:
	s_or_b64 exec, exec, s[2:3]
	s_load_dwordx16 s[44:59], s[0:1], 0x0
	s_lshr_b32 s0, s14, 6
	s_add_u32 s2, s92, 0x6000000
	s_addc_u32 s3, s93, 0
	s_add_u32 s4, s92, 0x8800000
	s_addc_u32 s5, s93, 0
	v_writelane_b32 v255, s4, 14
	v_lshlrev_b32_e32 v201, 3, v168
	s_waitcnt lgkmcnt(0)
	v_writelane_b32 v255, s5, 15
	s_add_u32 s4, s92, 0x9400000
	s_addc_u32 s5, s93, 0
	v_writelane_b32 v255, s4, 16
	s_barrier
	s_nop 0
	v_writelane_b32 v255, s5, 17
	s_add_u32 s4, s92, 0xb400000
	s_addc_u32 s5, s93, 0
	v_writelane_b32 v255, s4, 18
	s_add_u32 s8, s92, 0xbc00000
	s_addc_u32 s9, s93, 0
	v_writelane_b32 v255, s5, 19
	s_nop 0
	v_readlane_b32 s1, v255, 13
	s_lshl_b32 s1, s1, 3
	s_add_i32 s6, s0, s1
	v_writelane_b32 v255, s1, 20
	s_nop 0
	v_readlane_b32 s4, v255, 9
	v_readlane_b32 s5, v255, 10
	s_lshl_b32 s4, s4, 3
	v_writelane_b32 v255, s4, 21
	s_cmpk_gt_i32 s6, 0x5c7f
	s_nop 0
	v_writelane_b32 v255, s5, 22
	s_mov_b32 s4, s6
	v_writelane_b32 v255, s4, 23
	s_nop 1
	v_writelane_b32 v255, s5, 24
	v_readlane_b32 s60, v255, 23
	v_readlane_b32 s61, v255, 21
	v_readlane_b32 s82, v255, 2
	v_readlane_b32 s83, v255, 3
	v_readlane_b32 s84, v255, 14
	v_readlane_b32 s85, v255, 15
	v_readlane_b32 s86, v255, 16
	v_readlane_b32 s87, v255, 17
	v_readlane_b32 s88, v255, 18
	v_readlane_b32 s89, v255, 19
	v_and_b32_e32 v1, 63, v168
	v_readfirstlane_b32 s90, v168
	v_and_b32_e32 v252, 15, v1
	v_lshlrev_b32_e32 v2, 4, v252
	v_lshrrev_b32_e32 v253, 4, v1
	v_lshlrev_b32_e32 v68, 4, v253
	v_lshrrev_b32_e32 v69, 3, v1
	v_and_b32_e32 v254, 7, v1
	v_lshlrev_b32_e32 v128, 4, v254
	v_lshlrev_b32_e32 v170, 5, v1
	v_lshlrev_b32_e32 v171, 4, v1
	s_lshr_b32 s90, s90, 6
	s_lshl_b32 s90, s90, 13
	v_lshlrev_b32_e32 v180, 1, v253
	v_and_b32_e32 v181, 7, v252
	v_xor_b32_e32 v180, v180, v181
	v_lshlrev_b32_e32 v180, 4, v180
	v_lshl_add_u32 v180, v252, 9, v180
	v_add_u32_e32 v180, s90, v180
	v_xor_b32_e32 v181, 16, v180
	v_lshrrev_b32_e32 v252, 5, v1
	v_xor_b32_e32 v252, v254, v252
	v_lshlrev_b32_e32 v252, 4, v252
	v_lshl_add_u32 v252, v69, 7, v252
	v_add_u32_e32 v182, s90, v252
	v_xor_b32_e32 v200, 32, v182
	v_xor_b32_e32 v202, 64, v182
	v_xor_b32_e32 v203, 0x60, v182
	s_cmp_lt_u32 s60, 24128
	s_cbranch_scc0 .Lp0_done
	s_mov_b32 s62, s60
	s_cmp_lt_u32 s62, 11840
	s_cbranch_scc0 .Lp0_dx_a0
	s_mov_b32 s75, 1
	s_cmp_lt_u32 s62, 5120
	s_cbranch_scc0 .Lp0_d2_a0
	s_and_b32 s29, s62, 31
	s_lshr_b32 s30, s62, 5
	s_mul_i32 s31, s29, 2621440
	s_lshl_b32 s32, s30, 8
	s_add_u32 s31, s31, s32
	s_add_u32 s64, s50, s31
	s_addc_u32 s65, s51, 0
	s_mov_b32 s66, 40960
	s_mul_i32 s31, s30, 262144
	s_lshl_b32 s32, s29, 7
	s_add_u32 s31, s31, s32
	s_add_u32 s72, s2, s31
	s_addc_u32 s73, s3, 0
	s_movk_i32 s74, 0x1000
	s_branch .Lp0_dd_a0
.Lp0_d2_a0:
	s_cmp_lt_u32 s62, 6656
	s_cbranch_scc0 .Lp0_d3_a0
	s_sub_u32 s28, s62, 5120
	s_lshr_b32 s30, s28, 4
	s_mul_hi_u32 s30, s30, 0xaaaaaaab
	s_lshr_b32 s30, s30, 1
	s_mul_i32 s29, s30, 48
	s_sub_u32 s29, s28, s29
	s_mul_i32 s31, s29, 524288
	s_lshl_b32 s32, s30, 8
	s_add_u32 s31, s31, s32
	s_add_u32 s64, s56, s31
	s_addc_u32 s65, s57, 0
	s_movk_i32 s66, 0x2000
	s_mul_i32 s31, s30, 393216
	s_lshl_b32 s32, s29, 7
	s_add_u32 s31, s31, s32
	s_add_u32 s72, s84, s31
	s_addc_u32 s73, s85, 0
	s_movk_i32 s74, 0x1800
	s_branch .Lp0_dd_a0
.Lp0_d3_a0:
	s_cmp_lt_u32 s62, 10752
	s_cbranch_scc0 .Lp0_d4_a0
	s_sub_u32 s28, s62, 6656
	s_and_b32 s29, s28, 31
	s_lshr_b32 s30, s28, 5
	s_mul_i32 s31, s29, 2097152
	s_lshl_b32 s32, s30, 8
	s_add_u32 s31, s31, s32
	s_add_u32 s64, s58, s31
	s_addc_u32 s65, s59, 0
	s_mov_b32 s66, 0x8000
	s_lshr_b32 s33, s30, 5
	s_and_b32 s34, s30, 31
	s_lshr_b32 s34, s34, 1
	s_lshl_b32 s34, s34, 1
	s_cmp_eq_u32 s33, 0
	s_cselect_b32 s35, 1, 0
	s_cmp_eq_u32 s33, 3
	s_cselect_b32 s35, 1, s35
	s_add_u32 s34, s34, s35
	s_lshl_b32 s34, s34, 8
	s_cmp_ge_u32 s33, 2
	s_cselect_b32 s35, 128, 0
	s_add_u32 s34, s34, s35
	s_and_b32 s35, s30, 1
	s_lshl_b32 s35, s35, 6
	s_add_u32 s34, s34, s35
	s_lshl_b32 s31, s34, 12
	s_lshl_b32 s32, s29, 7
	s_add_u32 s31, s31, s32
	s_add_u32 s72, s86, s31
	s_addc_u32 s73, s87, 0
	s_movk_i32 s74, 0x1000
	s_branch .Lp0_dd_a0
.Lp0_d4_a0:
	s_cmp_lt_u32 s62, 11776
	s_cbranch_scc0 .Lp0_d5_a0
	s_sub_u32 s28, s62, 10752
	s_and_b32 s29, s28, 31
	s_lshr_b32 s30, s28, 5
	s_mul_i32 s31, s29, 524288
	s_lshl_b32 s32, s30, 8
	s_add_u32 s31, s31, s32
	s_add_u32 s64, s82, s31
	s_addc_u32 s65, s83, 0
	s_movk_i32 s66, 0x2000
	s_mul_i32 s31, s30, 262144
	s_lshl_b32 s32, s29, 7
	s_add_u32 s31, s31, s32
	s_add_u32 s72, s88, s31
	s_addc_u32 s73, s89, 0
	s_movk_i32 s74, 0x1000
	s_branch .Lp0_dd_a0

; __global__ void __launch_bounds__(512, 2) fwd_megakernel(Args a) {
;     ...
;         for (int it = gw; it < I1 + I2 + I3 + I4 + I5; it += NGW) {
;             int r = it;
;             if (r < I1) { const int kb = r / 320, nb = r % 320; transpose_item(w_in_ab, 10240, 64 * kb, 32 * nb, WT1, 2048, 32 * nb, scr, lane); continue; } r -= I1;
;             if (r < I2) { const int kb = r / 64, nb = r % 64; transpose_item(w_out_ab, 2048, 64 * kb, 32 * nb, WT2, 3072, 32 * nb, scr, lane); continue; } r -= I2;
;             if (r < I3) { const int kb = r / 256, nb = r % 256; const int n0 = 32 * nb, part = n0 >> 11, chn = n0 & 2047;
;                 const int type = (part == 0 || part == 3) ? 1 : 0, bj = (part >= 2) ? 1 : 0;
;                 const int drow = 256 * (2 * (chn >> 7) + type) + 128 * bj + (chn & 127);
;                 transpose_item(w_in_c, 8192, 64 * kb, n0, WT3, 2048, drow, scr, lane); continue; } r -= I3;
;             if (r < I4) { const int kb = r / 64, nb = r % 64; transpose_item(w_out_c, 2048, 64 * kb, 32 * nb, WT4, 2048, 32 * nb, scr, lane); continue; } r -= I4;
;             { const int gi = r >> 5, rr = r & 31, kb = rr >> 3, nb = rr & 7; transpose_item(pool_w + (size_t)gi * 65536, 256, 64 * kb, 32 * nb, WT5, 256, gi * 256 + 32 * nb, scr, lane); }
;         }
;         for (size_t i = gt; i < (size_t)MT * DM / 8; i += (size_t)NGT * 4) {
;             f32x4 v0[4], v1[4];
; #pragma unroll
;             for (int u = 0; u < 4; ++u) { const size_t ii = i + (size_t)u * NGT; if (ii < (size_t)MT * DM / 8) { const size_t e = ii * 8; const float* src = e < (size_t)MP * DM ? x_prompt + e : x_sample + (e - (size_t)MP * DM);
;                 v0[u] = *(const f32x4*)src; v1[u] = *(const f32x4*)(src + 4); } }
.Lp0_dd_a0:
	s_cmp_eq_u32 s75, 0
	s_cbranch_scc1 .Lp0_lx_a0
	v_mad_u32_u24 v130, v68, s66, v2
	global_load_dwordx4 v[80:83], v130, s[64:65] nt
	s_add_u32 s64, s64, s66
	s_addc_u32 s65, s65, 0
	global_load_dwordx4 v[84:87], v130, s[64:65] nt
	s_add_u32 s64, s64, s66
	s_addc_u32 s65, s65, 0
	global_load_dwordx4 v[92:95], v130, s[64:65] nt
	s_add_u32 s64, s64, s66
	s_addc_u32 s65, s65, 0
	global_load_dwordx4 v[96:99], v130, s[64:65] nt
	s_add_u32 s64, s64, s66
	s_addc_u32 s65, s65, 0
	global_load_dwordx4 v[100:103], v130, s[64:65] nt
	s_add_u32 s64, s64, s66
	s_addc_u32 s65, s65, 0
	global_load_dwordx4 v[104:107], v130, s[64:65] nt
	s_add_u32 s64, s64, s66
	s_addc_u32 s65, s65, 0
	global_load_dwordx4 v[108:111], v130, s[64:65] nt
	s_add_u32 s64, s64, s66
	s_addc_u32 s65, s65, 0
	global_load_dwordx4 v[112:115], v130, s[64:65] nt
	s_add_u32 s64, s64, s66
	s_addc_u32 s65, s65, 0
	global_load_dwordx4 v[116:119], v130, s[64:65] nt
	s_add_u32 s64, s64, s66
	s_addc_u32 s65, s65, 0
	global_load_dwordx4 v[136:139], v130, s[64:65] nt
	s_add_u32 s64, s64, s66
	s_addc_u32 s65, s65, 0
	global_load_dwordx4 v[140:143], v130, s[64:65] nt
	s_add_u32 s64, s64, s66
	s_addc_u32 s65, s65, 0
	global_load_dwordx4 v[144:147], v130, s[64:65] nt
	s_add_u32 s64, s64, s66
	s_addc_u32 s65, s65, 0
	global_load_dwordx4 v[148:151], v130, s[64:65] nt
	s_add_u32 s64, s64, s66
	s_addc_u32 s65, s65, 0
	global_load_dwordx4 v[152:155], v130, s[64:65] nt
	s_add_u32 s64, s64, s66
	s_addc_u32 s65, s65, 0
	global_load_dwordx4 v[156:159], v130, s[64:65] nt
	s_add_u32 s64, s64, s66
	s_addc_u32 s65, s65, 0
	global_load_dwordx4 v[160:163], v130, s[64:65] nt
	s_branch .Lp0_le_a0
.Lp0_lx_a0:
	global_load_dwordx4 v[80:83], v170, s[64:65] offset:0 nt
	global_load_dwordx4 v[84:87], v170, s[64:65] offset:16 nt
	global_load_dwordx4 v[92:95], v170, s[64:65] offset:2048 nt
	global_load_dwordx4 v[96:99], v170, s[64:65] offset:2064 nt
	s_add_u32 s64, s64, 0x1000
	s_addc_u32 s65, s65, 0
	global_load_dwordx4 v[100:103], v170, s[64:65] offset:0 nt
	global_load_dwordx4 v[104:107], v170, s[64:65] offset:16 nt
	global_load_dwordx4 v[108:111], v170, s[64:65] offset:2048 nt
	global_load_dwordx4 v[112:115], v170, s[64:65] offset:2064 nt
	s_add_u32 s64, s64, 0x1000
	s_addc_u32 s65, s65, 0
	global_load_dwordx4 v[116:119], v170, s[64:65] offset:0 nt
	global_load_dwordx4 v[136:139], v170, s[64:65] offset:16 nt
	global_load_dwordx4 v[140:143], v170, s[64:65] offset:2048 nt
	global_load_dwordx4 v[144:147], v170, s[64:65] offset:2064 nt
	s_add_u32 s64, s64, 0x1000
	s_addc_u32 s65, s65, 0
	global_load_dwordx4 v[148:151], v170, s[64:65] offset:0 nt
	global_load_dwordx4 v[152:155], v170, s[64:65] offset:16 nt
	global_load_dwordx4 v[156:159], v170, s[64:65] offset:2048 nt
	global_load_dwordx4 v[160:163], v170, s[64:65] offset:2064 nt
.Lp0_le_a0:
.Lp0_loop:
	s_add_u32 s60, s60, s61
	s_cmp_lt_u32 s60, 24128
	s_cbranch_scc0 .Lp0_nob
	s_mov_b32 s62, s60
	s_cmp_lt_u32 s62, 11840
	s_cbranch_scc0 .Lp0_dx_b
	s_mov_b32 s79, 1
	s_cmp_lt_u32 s62, 5120
	s_cbranch_scc0 .Lp0_d2_b
	s_and_b32 s29, s62, 31
	s_lshr_b32 s30, s62, 5
	s_mul_i32 s31, s29, 2621440
	s_lshl_b32 s32, s30, 8
	s_add_u32 s31, s31, s32
	s_add_u32 s64, s50, s31
	s_addc_u32 s65, s51, 0
	s_mov_b32 s66, 40960
	s_mul_i32 s31, s30, 262144
	s_lshl_b32 s32, s29, 7
	s_add_u32 s31, s31, s32
	s_add_u32 s76, s2, s31
	s_addc_u32 s77, s3, 0
	s_movk_i32 s78, 0x1000
	s_branch .Lp0_dd_b
.Lp0_d2_b:
	s_cmp_lt_u32 s62, 6656
	s_cbranch_scc0 .Lp0_d3_b
	s_sub_u32 s28, s62, 5120
	s_lshr_b32 s30, s28, 4
	s_mul_hi_u32 s30, s30, 0xaaaaaaab
	s_lshr_b32 s30, s30, 1
	s_mul_i32 s29, s30, 48
	s_sub_u32 s29, s28, s29
	s_mul_i32 s31, s29, 524288
	s_lshl_b32 s32, s30, 8
	s_add_u32 s31, s31, s32
	s_add_u32 s64, s56, s31
	s_addc_u32 s65, s57, 0
	s_movk_i32 s66, 0x2000
	s_mul_i32 s31, s30, 393216
	s_lshl_b32 s32, s29, 7
	s_add_u32 s31, s31, s32
	s_add_u32 s76, s84, s31
	s_addc_u32 s77, s85, 0
	s_movk_i32 s78, 0x1800
	s_branch .Lp0_dd_b
.Lp0_d3_b:
	s_cmp_lt_u32 s62, 10752
	s_cbranch_scc0 .Lp0_d4_b
	s_sub_u32 s28, s62, 6656
	s_and_b32 s29, s28, 31
	s_lshr_b32 s30, s28, 5
	s_mul_i32 s31, s29, 2097152
	s_lshl_b32 s32, s30, 8
	s_add_u32 s31, s31, s32
	s_add_u32 s64, s58, s31
	s_addc_u32 s65, s59, 0
	s_mov_b32 s66, 0x8000
	s_lshr_b32 s33, s30, 5
	s_and_b32 s34, s30, 31
	s_lshr_b32 s34, s34, 1
	s_lshl_b32 s34, s34, 1
	s_cmp_eq_u32 s33, 0
	s_cselect_b32 s35, 1, 0
	s_cmp_eq_u32 s33, 3
	s_cselect_b32 s35, 1, s35
	s_add_u32 s34, s34, s35
	s_lshl_b32 s34, s34, 8
	s_cmp_ge_u32 s33, 2
	s_cselect_b32 s35, 128, 0
	s_add_u32 s34, s34, s35
	s_and_b32 s35, s30, 1
	s_lshl_b32 s35, s35, 6
	s_add_u32 s34, s34, s35
	s_lshl_b32 s31, s34, 12
	s_lshl_b32 s32, s29, 7
	s_add_u32 s31, s31, s32
	s_add_u32 s76, s86, s31
	s_addc_u32 s77, s87, 0
	s_movk_i32 s78, 0x1000
	s_branch .Lp0_dd_b
.Lp0_d4_b:
	s_cmp_lt_u32 s62, 11776
	s_cbranch_scc0 .Lp0_d5_b
	s_sub_u32 s28, s62, 10752
	s_and_b32 s29, s28, 31
	s_lshr_b32 s30, s28, 5
	s_mul_i32 s31, s29, 524288
	s_lshl_b32 s32, s30, 8
	s_add_u32 s31, s31, s32
	s_add_u32 s64, s82, s31
	s_addc_u32 s65, s83, 0
	s_movk_i32 s66, 0x2000
	s_mul_i32 s31, s30, 262144
	s_lshl_b32 s32, s29, 7
	s_add_u32 s31, s31, s32
	s_add_u32 s76, s88, s31
	s_addc_u32 s77, s89, 0
	s_movk_i32 s78, 0x1000
	s_branch .Lp0_dd_b

; __global__ void __launch_bounds__(512, 2) fwd_megakernel(Args a) {
;     ...
;         for (size_t i = gt; i < (size_t)MT * DM / 8; i += (size_t)NGT * 4) {
;             f32x4 v0[4], v1[4];
; #pragma unroll
;             for (int u = 0; u < 4; ++u) { const size_t ii = i + (size_t)u * NGT; if (ii < (size_t)MT * DM / 8) { const size_t e = ii * 8; const float* src = e < (size_t)MP * DM ? x_prompt + e : x_sample + (e - (size_t)MP * DM);
;                 v0[u] = *(const f32x4*)src; v1[u] = *(const f32x4*)(src + 4); } }
.Lp0_dd_b:
	s_cmp_eq_u32 s79, 0
	s_cbranch_scc1 .Lp0_lx_b
	v_mad_u32_u24 v130, v68, s66, v2
	global_load_dwordx4 v[184:187], v130, s[64:65] nt
	s_add_u32 s64, s64, s66
	s_addc_u32 s65, s65, 0
	global_load_dwordx4 v[188:191], v130, s[64:65] nt
	s_add_u32 s64, s64, s66
	s_addc_u32 s65, s65, 0
	global_load_dwordx4 v[192:195], v130, s[64:65] nt
	s_add_u32 s64, s64, s66
	s_addc_u32 s65, s65, 0
	global_load_dwordx4 v[196:199], v130, s[64:65] nt
	s_add_u32 s64, s64, s66
	s_addc_u32 s65, s65, 0
	global_load_dwordx4 v[204:207], v130, s[64:65] nt
	s_add_u32 s64, s64, s66
	s_addc_u32 s65, s65, 0
	global_load_dwordx4 v[208:211], v130, s[64:65] nt
	s_add_u32 s64, s64, s66
	s_addc_u32 s65, s65, 0
	global_load_dwordx4 v[212:215], v130, s[64:65] nt
	s_add_u32 s64, s64, s66
	s_addc_u32 s65, s65, 0
	global_load_dwordx4 v[216:219], v130, s[64:65] nt
	s_add_u32 s64, s64, s66
	s_addc_u32 s65, s65, 0
	global_load_dwordx4 v[220:223], v130, s[64:65] nt
	s_add_u32 s64, s64, s66
	s_addc_u32 s65, s65, 0
	global_load_dwordx4 v[224:227], v130, s[64:65] nt
	s_add_u32 s64, s64, s66
	s_addc_u32 s65, s65, 0
	global_load_dwordx4 v[228:231], v130, s[64:65] nt
	s_add_u32 s64, s64, s66
	s_addc_u32 s65, s65, 0
	global_load_dwordx4 v[232:235], v130, s[64:65] nt
	s_add_u32 s64, s64, s66
	s_addc_u32 s65, s65, 0
	global_load_dwordx4 v[236:239], v130, s[64:65] nt
	s_add_u32 s64, s64, s66
	s_addc_u32 s65, s65, 0
	global_load_dwordx4 v[240:243], v130, s[64:65] nt
	s_add_u32 s64, s64, s66
	s_addc_u32 s65, s65, 0
	global_load_dwordx4 v[244:247], v130, s[64:65] nt
	s_add_u32 s64, s64, s66
	s_addc_u32 s65, s65, 0
	global_load_dwordx4 v[248:251], v130, s[64:65] nt
	s_branch .Lp0_le_b
.Lp0_lx_b:
	global_load_dwordx4 v[184:187], v170, s[64:65] offset:0 nt
	global_load_dwordx4 v[188:191], v170, s[64:65] offset:16 nt
	global_load_dwordx4 v[192:195], v170, s[64:65] offset:2048 nt
	global_load_dwordx4 v[196:199], v170, s[64:65] offset:2064 nt
	s_add_u32 s64, s64, 0x1000
	s_addc_u32 s65, s65, 0
	global_load_dwordx4 v[204:207], v170, s[64:65] offset:0 nt
	global_load_dwordx4 v[208:211], v170, s[64:65] offset:16 nt
	global_load_dwordx4 v[212:215], v170, s[64:65] offset:2048 nt
	global_load_dwordx4 v[216:219], v170, s[64:65] offset:2064 nt
	s_add_u32 s64, s64, 0x1000
	s_addc_u32 s65, s65, 0
	global_load_dwordx4 v[220:223], v170, s[64:65] offset:0 nt
	global_load_dwordx4 v[224:227], v170, s[64:65] offset:16 nt
	global_load_dwordx4 v[228:231], v170, s[64:65] offset:2048 nt
	global_load_dwordx4 v[232:235], v170, s[64:65] offset:2064 nt
	s_add_u32 s64, s64, 0x1000
	s_addc_u32 s65, s65, 0
	global_load_dwordx4 v[236:239], v170, s[64:65] offset:0 nt
	global_load_dwordx4 v[240:243], v170, s[64:65] offset:16 nt
	global_load_dwordx4 v[244:247], v170, s[64:65] offset:2048 nt
	global_load_dwordx4 v[248:251], v170, s[64:65] offset:2064 nt

; __global__ void __launch_bounds__(512, 2) fwd_megakernel(Args a) {
;     ...
;         for (int it = gw; it < I1 + I2 + I3 + I4 + I5; it += NGW) {
;             int r = it;
;             if (r < I1) { const int kb = r / 320, nb = r % 320; transpose_item(w_in_ab, 10240, 64 * kb, 32 * nb, WT1, 2048, 32 * nb, scr, lane); continue; } r -= I1;
;             if (r < I2) { const int kb = r / 64, nb = r % 64; transpose_item(w_out_ab, 2048, 64 * kb, 32 * nb, WT2, 3072, 32 * nb, scr, lane); continue; } r -= I2;
;             if (r < I3) { const int kb = r / 256, nb = r % 256; const int n0 = 32 * nb, part = n0 >> 11, chn = n0 & 2047;
.Lp0_pe_a:
	s_cmp_lt_u32 s60, 24128
	s_cbranch_scc0 .Lp0_done
	s_add_u32 s60, s60, s61
	s_cmp_lt_u32 s60, 24128
	s_cbranch_scc0 .Lp0_noa
	s_mov_b32 s62, s60
	s_cmp_lt_u32 s62, 11840
	s_cbranch_scc0 .Lp0_dx_a1
	s_mov_b32 s75, 1
	s_cmp_lt_u32 s62, 5120
	s_cbranch_scc0 .Lp0_d2_a1
	s_and_b32 s29, s62, 31
	s_lshr_b32 s30, s62, 5
	s_mul_i32 s31, s29, 2621440
	s_lshl_b32 s32, s30, 8
	s_add_u32 s31, s31, s32
	s_add_u32 s64, s50, s31
	s_addc_u32 s65, s51, 0
	s_mov_b32 s66, 40960
	s_mul_i32 s31, s30, 262144
	s_lshl_b32 s32, s29, 7
	s_add_u32 s31, s31, s32
	s_add_u32 s72, s2, s31
	s_addc_u32 s73, s3, 0
	s_movk_i32 s74, 0x1000
	s_branch .Lp0_dd_a1

;     ...
;         for (int i = 0; i < 8; ++i) { const int r = r0 + 32 * i;
;             *(LAS u32x4*)(lds + KOFF + r * PITCH + ch * 16) = kv[i]; *(LAS u32x4*)(lds + VOFF + r * VPITCH + ch * 16) = vv[i]; }
;         if (!hoist) { if (tid < 200) { const int bi = tid - 32; bias[tid] = (bi >= 0 && bi <= 128) ? rel_bias[t5_bucket((bi - 64) * D) * 16 + h] * LOG2E : -1.0e30f; } }
;         bf16x8 qf[4];
; #pragma unroll
;         for (int kk = 0; kk < 4; ++kk) qf[kk] = qn[kk];
;         const int qrow = seq_base + (qb * 128 + 16 * w + fr) * D + g;
;         asm volatile("s_waitcnt lgkmcnt(0)\n\ts_barrier" ::: "memory");
;         if (item + item_step < item_end) { const int nit = item + item_step; ATT_DECODE(nit) ATT_LOAD(); }
;         const int ts = w & ~1;
;         f32x4 s[10];
;         {
;             LAS const unsigned char* kptr = lds + KOFF + (16 * ts + fr) * PITCH + fq * 16;
;             bf16x8 kf[2][2][4];
;     ...
;         const float rl = 1.0f / l;
;         float Lc = mx + __builtin_amdgcn_logf(l);
;         float wb = rl, wa = 0.f;
;         if (PASS > 0) { const float Lm = fmaxf(Lp, Lc);
;             const float ea = __builtin_amdgcn_exp2f(Lp - Lm), eb = __builtin_amdgcn_exp2f(Lc - Lm), den = ea + eb, rd = 1.0f / den;
;             wa = ea * rd; wb = eb * rd * rl; Lc = Lm + __builtin_amdgcn_logf(den); }
;         if (PASS < 2) { if (fq == 0) LACC[(size_t)qrow * 16 + h] = Lc; }
; #pragma unroll
;         for (int db = 0; db < 8; ++db) { f32x4 v = o[db] * wb;
;             const size_t ocol = (size_t)h * 128 + 16 * db + 4 * fq;
;             if (PASS > 0) { v[0] += wa * bf_lo(pv[db].x); v[1] += wa * bf_hi(pv[db].x); v[2] += wa * bf_lo(pv[db].y); v[3] += wa * bf_hi(pv[db].y); }
;             if (PASS < 2) { u32x2 ov; ov.x = pg8::cvt_pk_bf16(v[0], v[1]); ov.y = pg8::cvt_pk_bf16(v[2], v[3]); *(u32x2*)((char*)OACC + ((unsigned)(h * MT + qrow) * 256u + (unsigned)(32 * db + 8 * fq))) = ov; }
;             else { v[0] *= pg8::silu_f(bf_lo(gv[db].x)); v[1] *= pg8::silu_f(bf_hi(gv[db].x)); v[2] *= pg8::silu_f(bf_lo(gv[db].y)); v[3] *= pg8::silu_f(bf_hi(gv[db].y));
;                 u32x2 ov; ov.x = pg8::cvt_pk_bf16(v[0], v[1]); ov.y = pg8::cvt_pk_bf16(v[2], v[3]); *(u32x2*)((char*)RB + ((unsigned)qrow * (unsigned)(LDB * 2) + (unsigned)(h * 256 + 32 * db + 8 * fq))) = ov; } }
;         asm volatile("s_waitcnt lgkmcnt(0)\n\ts_barrier" ::: "memory");
.LBB0_263:
	s_or_b64 exec, exec, s[0:1]
	v_div_scale_f32 v85, s[0:1], v84, v84, 1.0
	v_rcp_f32_e32 v86, v85
	v_div_scale_f32 v87, vcc, 1.0, v84, 1.0
	s_addk_i32 s23, 0x80
	v_fma_f32 v88, -v85, v86, 1.0
	v_fmac_f32_e32 v86, v88, v86
	v_mul_f32_e32 v88, v87, v86
	v_fma_f32 v89, -v85, v88, v87
	v_fmac_f32_e32 v88, v89, v86
	v_fma_f32 v85, -v85, v88, v87
	v_div_fmas_f32 v85, v85, v86, v88
	v_div_fixup_f32 v84, v85, v84, 1.0
	v_and_b32_e32 v86, 16, v168
	v_lshrrev_b32_e32 v87, 1, v86
	v_add3_u32 v88, v225, v86, v87
	v_pk_mul_f32 v[100:101], v[84:85], v[100:101] op_sel_hi:[0,1]
	v_pk_mul_f32 v[102:103], v[84:85], v[102:103] op_sel_hi:[0,1]
	v_pk_mul_f32 v[104:105], v[84:85], v[104:105] op_sel_hi:[0,1]
	v_pk_mul_f32 v[106:107], v[84:85], v[106:107] op_sel_hi:[0,1]
	v_cvt_pk_bf16_f32 v100, v100, v101
	v_cvt_pk_bf16_f32 v101, v102, v103
	v_cvt_pk_bf16_f32 v102, v104, v105
	v_cvt_pk_bf16_f32 v103, v106, v107
	s_nop 1
	v_permlane16_swap_b32_e32 v100, v102
	v_permlane16_swap_b32_e32 v101, v103
	global_store_dwordx4 v88, v[100:103], s[92:93]
	v_pk_mul_f32 v[108:109], v[84:85], v[108:109] op_sel_hi:[0,1]
	v_pk_mul_f32 v[110:111], v[84:85], v[110:111] op_sel_hi:[0,1]
	v_pk_mul_f32 v[112:113], v[84:85], v[112:113] op_sel_hi:[0,1]
	v_pk_mul_f32 v[114:115], v[84:85], v[114:115] op_sel_hi:[0,1]
	v_cvt_pk_bf16_f32 v108, v108, v109
	v_cvt_pk_bf16_f32 v109, v110, v111
	v_cvt_pk_bf16_f32 v110, v112, v113
	v_cvt_pk_bf16_f32 v111, v114, v115
	s_nop 1
	v_permlane16_swap_b32_e32 v108, v110
	v_permlane16_swap_b32_e32 v109, v111
	global_store_dwordx4 v88, v[108:111], s[92:93] offset:64
	v_pk_mul_f32 v[116:117], v[84:85], v[116:117] op_sel_hi:[0,1]
	v_pk_mul_f32 v[118:119], v[84:85], v[118:119] op_sel_hi:[0,1]
	v_pk_mul_f32 v[120:121], v[84:85], v[120:121] op_sel_hi:[0,1]
	v_pk_mul_f32 v[122:123], v[84:85], v[122:123] op_sel_hi:[0,1]
	v_cvt_pk_bf16_f32 v116, v116, v117
	v_cvt_pk_bf16_f32 v117, v118, v119
	v_cvt_pk_bf16_f32 v118, v120, v121
	v_cvt_pk_bf16_f32 v119, v122, v123
	s_nop 1
	v_permlane16_swap_b32_e32 v116, v118
	v_permlane16_swap_b32_e32 v117, v119
	global_store_dwordx4 v88, v[116:119], s[92:93] offset:128
	v_pk_mul_f32 v[124:125], v[84:85], v[124:125] op_sel_hi:[0,1]
	v_pk_mul_f32 v[126:127], v[84:85], v[126:127] op_sel_hi:[0,1]
	v_pk_mul_f32 v[80:81], v[84:85], v[80:81] op_sel_hi:[0,1]
	v_pk_mul_f32 v[82:83], v[84:85], v[82:83] op_sel_hi:[0,1]
	v_cvt_pk_bf16_f32 v124, v124, v125
	v_cvt_pk_bf16_f32 v125, v126, v127
	v_cvt_pk_bf16_f32 v126, v80, v81
	v_cvt_pk_bf16_f32 v127, v82, v83
	s_nop 1
	v_permlane16_swap_b32_e32 v124, v126
	v_permlane16_swap_b32_e32 v125, v127
	global_store_dwordx4 v88, v[124:127], s[92:93] offset:192
	s_waitcnt lgkmcnt(0)
	s_barrier
	v_add_u32_e32 v189, 0x8000, v189
	s_cmpk_lg_i32 s23, 0x180
	v_add_u32_e32 v225, 0x8000, v225
	s_cbranch_scc0 .LBB0_265
	s_waitcnt vmcnt(4)
	v_mov_b64_e32 v[122:123], v[2:3]
	v_mov_b64_e32 v[126:127], v[22:23]
	v_mov_b64_e32 v[130:131], v[18:19]
	v_mov_b64_e32 v[134:135], v[14:15]
	v_mov_b64_e32 v[120:121], v[0:1]
	v_mov_b64_e32 v[124:125], v[20:21]
	v_mov_b64_e32 v[128:129], v[16:17]
	v_mov_b64_e32 v[132:133], v[12:13]
	s_branch .LBB0_169
.LBB0_265:
	s_waitcnt vmcnt(23)
	ds_write_b128 v216, v[8:11]
	s_waitcnt vmcnt(22)
	ds_write_b128 v217, v[4:7]
	s_waitcnt vmcnt(21)
	ds_write_b128 v216, v[28:31] offset:8704
	s_waitcnt vmcnt(20)
	ds_write_b128 v217, v[24:27] offset:9216
	s_waitcnt vmcnt(19)
	ds_write_b128 v216, v[36:39] offset:17408
	s_waitcnt vmcnt(18)
	ds_write_b128 v217, v[32:35] offset:18432
	s_waitcnt vmcnt(17)
	ds_write_b128 v216, v[44:47] offset:26112
	s_waitcnt vmcnt(16)
	ds_write_b128 v217, v[40:43] offset:27648
	s_waitcnt vmcnt(15)
	ds_write_b128 v216, v[52:55] offset:34816
	s_waitcnt vmcnt(14)
	ds_write_b128 v217, v[48:51] offset:36864
	s_waitcnt vmcnt(13)
	ds_write_b128 v216, v[60:63] offset:43520
	s_waitcnt vmcnt(12)
	ds_write_b128 v217, v[56:59] offset:46080
	s_waitcnt vmcnt(11)
	ds_write_b128 v216, v[68:71] offset:52224
	s_waitcnt vmcnt(10)
	ds_write_b128 v217, v[64:67] offset:55296
	s_waitcnt vmcnt(9)
	ds_write_b128 v216, v[76:79] offset:60928
	s_waitcnt vmcnt(8)
	ds_write_b128 v217, v[72:75] offset:64512
	s_waitcnt lgkmcnt(0)
	s_barrier
	ds_read_b128 v[68:71], v190
	ds_read_b128 v[64:67], v190 offset:64
	ds_read_b128 v[60:63], v190 offset:128
	ds_read_b128 v[56:59], v190 offset:192
	ds_read_b128 v[84:87], v190 offset:4352
	ds_read_b128 v[80:83], v190 offset:4416
	ds_read_b128 v[76:79], v190 offset:4480
	ds_read_b128 v[72:75], v190 offset:4544
	ds_read_b128 v[32:35], v190 offset:8704
	ds_read_b128 v[24:27], v190 offset:8768
	ds_read_b128 v[8:11], v190 offset:8832
	ds_read_b128 v[4:7], v190 offset:8896
	ds_read_b128 v[52:55], v190 offset:13056
	ds_read_b128 v[48:51], v190 offset:13120
	ds_read_b128 v[40:43], v190 offset:13184
	ds_read_b128 v[36:39], v190 offset:13248
	s_and_b64 vcc, exec, s[8:9]
	s_mov_b64 s[0:1], -1
	s_cbranch_vccnz .LBB0_267
	s_waitcnt vmcnt(7) lgkmcnt(11)
	v_mfma_f32_16x16x32_bf16 v[28:31], v[84:87], v[12:15], 0
	s_mov_b64 s[0:1], 0
	s_waitcnt vmcnt(6) lgkmcnt(10)
	v_mfma_f32_16x16x32_bf16 v[28:31], v[80:83], v[16:19], v[28:31]
	s_waitcnt vmcnt(5) lgkmcnt(9)
	v_mfma_f32_16x16x32_bf16 v[28:31], v[76:79], v[20:23], v[28:31]
	s_waitcnt vmcnt(4) lgkmcnt(8)
	v_mfma_f32_16x16x32_bf16 v[28:31], v[72:75], v[0:3], v[28:31]
; #define LAS __attribute__((address_space(3)))
; #define ATT_LDK(BUF, TP) _Pragma("unroll") for (int u = 0; u < 2; ++u) _Pragma("unroll") for (int kk = 0; kk < 4; ++kk) kf[BUF][u][kk] = *(const LAS bf16x8*)(kptr + (16 * (2 * (TP) + u)) * PITCH + kk * 64);
;     ...
;         {
;             LAS const unsigned char* kptr = lds + KOFF + (16 * ts + fr) * PITCH + fq * 16;
;             bf16x8 kf[2][2][4];
;     ...
;             ATT_LDK(0, 0)
; #pragma unroll
;             for (int tp = 0; tp < 5; ++tp) {
;                 if (tp + 1 < 5) { ATT_LDK((tp + 1) & 1, tp + 1) }
;                 __builtin_amdgcn_sched_barrier(0);
;                 s[2 * tp] = (f32x4){0.f, 0.f, 0.f, 0.f}; s[2 * tp + 1] = (f32x4){0.f, 0.f, 0.f, 0.f};
;                 if (tp == 0 && (w & 1)) {
; #pragma unroll
;                     for (int kk = 0; kk < 4; ++kk) s[1] = __builtin_amdgcn_mfma_f32_16x16x32_bf16(kf[0][1][kk], qf[kk], s[1], 0, 0, 0);
;                 } else if (tp == 4 && !(w & 1)) {
; #pragma unroll
;                     for (int kk = 0; kk < 4; ++kk) s[8] = __builtin_amdgcn_mfma_f32_16x16x32_bf16(kf[0][0][kk], qf[kk], s[8], 0, 0, 0);
;                 } else {
; #pragma unroll
;                 for (int kk = 0; kk < 4; ++kk) { s[2 * tp] = __builtin_amdgcn_mfma_f32_16x16x32_bf16(kf[tp & 1][0][kk], qf[kk], s[2 * tp], 0, 0, 0);
;                     s[2 * tp + 1] = __builtin_amdgcn_mfma_f32_16x16x32_bf16(kf[tp & 1][1][kk], qf[kk], s[2 * tp + 1], 0, 0, 0); } }
;                 __builtin_amdgcn_sched_barrier(0);
;             }
;     ...
;         }
.LBB0_267:
	v_mov_b32_e32 v44, 0
	s_andn2_b64 vcc, exec, s[0:1]
	v_mov_b32_e32 v45, 0
	v_mov_b32_e32 v46, 0
	v_mov_b32_e32 v47, 0
	s_cbranch_vccnz .LBB0_269
	s_waitcnt vmcnt(7) lgkmcnt(14)
	v_mfma_f32_16x16x32_bf16 v[28:31], v[68:71], v[12:15], 0
	s_waitcnt lgkmcnt(11)
	v_mfma_f32_16x16x32_bf16 v[44:47], v[84:87], v[12:15], 0
	s_waitcnt vmcnt(6)
	v_mfma_f32_16x16x32_bf16 v[28:31], v[64:67], v[16:19], v[28:31]
	s_waitcnt lgkmcnt(10)
	v_mfma_f32_16x16x32_bf16 v[44:47], v[80:83], v[16:19], v[44:47]
	s_waitcnt vmcnt(5)
	v_mfma_f32_16x16x32_bf16 v[28:31], v[60:63], v[20:23], v[28:31]
	s_waitcnt lgkmcnt(9)
	v_mfma_f32_16x16x32_bf16 v[60:63], v[76:79], v[20:23], v[44:47]
	s_waitcnt vmcnt(4)
	v_mfma_f32_16x16x32_bf16 v[44:47], v[56:59], v[0:3], v[28:31]
	s_waitcnt lgkmcnt(8)
	v_mfma_f32_16x16x32_bf16 v[28:31], v[72:75], v[0:3], v[60:63]
.LBB0_269:
	s_waitcnt lgkmcnt(12)
	ds_read_b128 v[56:59], v190 offset:17408
	s_nop 1
	ds_read_b128 v[60:63], v190 offset:17472
	ds_read_b128 v[64:67], v190 offset:17536
	ds_read_b128 v[68:71], v190 offset:17600
	s_waitcnt lgkmcnt(12)
	ds_read_b128 v[72:75], v190 offset:21760
	ds_read_b128 v[76:79], v190 offset:21824
	ds_read_b128 v[80:83], v190 offset:21888
	ds_read_b128 v[84:87], v190 offset:21952
	s_waitcnt vmcnt(7) lgkmcnt(14)
	v_mfma_f32_16x16x32_bf16 v[32:35], v[32:35], v[12:15], 0
	s_waitcnt lgkmcnt(11)
	v_mfma_f32_16x16x32_bf16 v[52:55], v[52:55], v[12:15], 0
	s_waitcnt vmcnt(6)
	v_mfma_f32_16x16x32_bf16 v[24:27], v[24:27], v[16:19], v[32:35]
	s_waitcnt lgkmcnt(10)
	v_mfma_f32_16x16x32_bf16 v[32:35], v[48:51], v[16:19], v[52:55]
	s_waitcnt vmcnt(5)
	v_mfma_f32_16x16x32_bf16 v[8:11], v[8:11], v[20:23], v[24:27]
	s_waitcnt lgkmcnt(9)
	v_mfma_f32_16x16x32_bf16 v[24:27], v[40:43], v[20:23], v[32:35]
	s_waitcnt vmcnt(4)
	v_mfma_f32_16x16x32_bf16 v[52:55], v[4:7], v[0:3], v[8:11]
	s_waitcnt lgkmcnt(8)
	v_mfma_f32_16x16x32_bf16 v[48:51], v[36:39], v[0:3], v[24:27]
	ds_read_b128 v[4:7], v190 offset:26112
	s_nop 0
	ds_read_b128 v[8:11], v190 offset:26176
	s_nop 0
	ds_read_b128 v[24:27], v190 offset:26240
	ds_read_b128 v[32:35], v190 offset:26304
	ds_read_b128 v[88:91], v190 offset:30464
	ds_read_b128 v[92:95], v190 offset:30528
	ds_read_b128 v[96:99], v190 offset:30592
	ds_read_b128 v[100:103], v190 offset:30656
	s_waitcnt lgkmcnt(14)
	v_mfma_f32_16x16x32_bf16 v[36:39], v[56:59], v[12:15], 0
	s_waitcnt lgkmcnt(11)
	v_mfma_f32_16x16x32_bf16 v[40:43], v[72:75], v[12:15], 0
	v_mfma_f32_16x16x32_bf16 v[36:39], v[60:63], v[16:19], v[36:39]
	s_waitcnt lgkmcnt(10)
	v_mfma_f32_16x16x32_bf16 v[40:43], v[76:79], v[16:19], v[40:43]
	v_mfma_f32_16x16x32_bf16 v[36:39], v[64:67], v[20:23], v[36:39]
	s_waitcnt lgkmcnt(9)
	v_mfma_f32_16x16x32_bf16 v[56:59], v[80:83], v[20:23], v[40:43]
	v_mfma_f32_16x16x32_bf16 v[40:43], v[68:71], v[0:3], v[36:39]
	s_waitcnt lgkmcnt(8)
	v_mfma_f32_16x16x32_bf16 v[36:39], v[84:87], v[0:3], v[56:59]
	ds_read_b128 v[60:63], v190 offset:34816
	ds_read_b128 v[64:67], v190 offset:34880
	ds_read_b128 v[68:71], v190 offset:34944
	s_nop 1
	ds_read_b128 v[56:59], v190 offset:35008
	ds_read_b128 v[84:87], v190 offset:39168
	ds_read_b128 v[80:83], v190 offset:39232
	ds_read_b128 v[76:79], v190 offset:39296
	ds_read_b128 v[72:75], v190 offset:39360
	s_waitcnt lgkmcnt(14)
	v_mfma_f32_16x16x32_bf16 v[4:7], v[4:7], v[12:15], 0
	s_waitcnt lgkmcnt(11)
	v_mfma_f32_16x16x32_bf16 v[88:91], v[88:91], v[12:15], 0
	v_mfma_f32_16x16x32_bf16 v[4:7], v[8:11], v[16:19], v[4:7]
	s_waitcnt lgkmcnt(10)
	v_mfma_f32_16x16x32_bf16 v[8:11], v[92:95], v[16:19], v[88:91]
	v_mfma_f32_16x16x32_bf16 v[4:7], v[24:27], v[20:23], v[4:7]
	s_waitcnt lgkmcnt(9)
	v_mfma_f32_16x16x32_bf16 v[8:11], v[96:99], v[20:23], v[8:11]
	v_mfma_f32_16x16x32_bf16 v[32:35], v[32:35], v[0:3], v[4:7]
	s_waitcnt lgkmcnt(8)
	v_mfma_f32_16x16x32_bf16 v[8:11], v[100:103], v[0:3], v[8:11]
	s_and_b64 vcc, exec, s[8:9]
	s_mov_b64 s[0:1], -1
	s_cbranch_vccnz .LBB0_271
	s_waitcnt lgkmcnt(7)
	v_mfma_f32_16x16x32_bf16 v[4:7], v[60:63], v[12:15], 0
	s_mov_b64 s[0:1], 0
	s_waitcnt lgkmcnt(3)
	v_mfma_f32_16x16x32_bf16 v[24:27], v[84:87], v[12:15], 0
	v_mfma_f32_16x16x32_bf16 v[4:7], v[64:67], v[16:19], v[4:7]
	s_waitcnt lgkmcnt(2)
	v_mfma_f32_16x16x32_bf16 v[24:27], v[80:83], v[16:19], v[24:27]
	v_mfma_f32_16x16x32_bf16 v[4:7], v[68:71], v[20:23], v[4:7]
	s_waitcnt lgkmcnt(1)
	v_mfma_f32_16x16x32_bf16 v[76:79], v[76:79], v[20:23], v[24:27]
	v_mfma_f32_16x16x32_bf16 v[24:27], v[56:59], v[0:3], v[4:7]
	s_waitcnt lgkmcnt(0)
	v_mfma_f32_16x16x32_bf16 v[4:7], v[72:75], v[0:3], v[76:79]

; __device__ __forceinline__ unsigned cvt_pk_bf16(float lo, float hi) { unsigned r; asm volatile("v_cvt_pk_bf16_f32 %0, %1, %2" : "=v"(r) : "v"(lo), "v"(hi)); return r; }
; __device__ __forceinline__ float silu_f(float x) { return x * __builtin_amdgcn_rcpf(1.0f + __builtin_amdgcn_exp2f(-x * LOG2E)); }
;     ...
;     if (hoist && tid < 200) { const int bi = tid - 32; bias[tid] = (bi >= 0 && bi <= 128) ? rel_bias[t5_bucket((bi - 64) * D) * 16 + (SB ? sb_h : (item & 15))] * LOG2E : -1.0e30f; }
;     ...
;         const float rl = 1.0f / l;
;         float Lc = mx + __builtin_amdgcn_logf(l);
;         float wb = rl, wa = 0.f;
;         if (PASS > 0) { const float Lm = fmaxf(Lp, Lc);
;             const float ea = __builtin_amdgcn_exp2f(Lp - Lm), eb = __builtin_amdgcn_exp2f(Lc - Lm), den = ea + eb, rd = 1.0f / den;
;             wa = ea * rd; wb = eb * rd * rl; Lc = Lm + __builtin_amdgcn_logf(den); }
;         if (PASS < 2) { if (fq == 0) LACC[(size_t)qrow * 16 + h] = Lc; }
; #pragma unroll
;         for (int db = 0; db < 8; ++db) { f32x4 v = o[db] * wb;
;             const size_t ocol = (size_t)h * 128 + 16 * db + 4 * fq;
;             if (PASS > 0) { v[0] += wa * bf_lo(pv[db].x); v[1] += wa * bf_hi(pv[db].x); v[2] += wa * bf_lo(pv[db].y); v[3] += wa * bf_hi(pv[db].y); }
;             if (PASS < 2) { u32x2 ov; ov.x = pg8::cvt_pk_bf16(v[0], v[1]); ov.y = pg8::cvt_pk_bf16(v[2], v[3]); *(u32x2*)((char*)OACC + ((unsigned)(h * MT + qrow) * 256u + (unsigned)(32 * db + 8 * fq))) = ov; }
;             else { v[0] *= pg8::silu_f(bf_lo(gv[db].x)); v[1] *= pg8::silu_f(bf_hi(gv[db].x)); v[2] *= pg8::silu_f(bf_lo(gv[db].y)); v[3] *= pg8::silu_f(bf_hi(gv[db].y));
;                 u32x2 ov; ov.x = pg8::cvt_pk_bf16(v[0], v[1]); ov.y = pg8::cvt_pk_bf16(v[2], v[3]); *(u32x2*)((char*)RB + ((unsigned)qrow * (unsigned)(LDB * 2) + (unsigned)(h * 256 + 32 * db + 8 * fq))) = ov; } }
;         asm volatile("s_waitcnt lgkmcnt(0)\n\ts_barrier" ::: "memory");
.LBB0_359:
	s_or_b64 exec, exec, s[0:1]
	v_div_scale_f32 v5, s[0:1], v4, v4, 1.0
	v_rcp_f32_e32 v6, v5
	v_div_scale_f32 v7, vcc, 1.0, v4, 1.0
	v_readfirstlane_b32 s73, v168
	v_fma_f32 v8, -v5, v6, 1.0
	v_fmac_f32_e32 v6, v8, v6
	v_mul_f32_e32 v8, v7, v6
	v_fma_f32 v9, -v5, v8, v7
	v_fmac_f32_e32 v8, v9, v6
	v_fma_f32 v5, -v5, v8, v7
	v_div_fmas_f32 v5, v5, v6, v8
	v_div_fixup_f32 v4, v5, v4, 1.0
	v_add_u32_e32 v5, s14, v48
	v_lshl_or_b32 v5, v5, 8, v210
	v_and_b32_e32 v6, 16, v168
	v_lshrrev_b32_e32 v7, 1, v6
	v_add3_u32 v8, v5, v6, v7
	v_pk_mul_f32 v[20:21], v[4:5], v[20:21] op_sel_hi:[0,1]
	v_pk_mul_f32 v[22:23], v[4:5], v[22:23] op_sel_hi:[0,1]
	v_pk_mul_f32 v[24:25], v[4:5], v[24:25] op_sel_hi:[0,1]
	v_pk_mul_f32 v[26:27], v[4:5], v[26:27] op_sel_hi:[0,1]
	v_cvt_pk_bf16_f32 v20, v20, v21
	v_cvt_pk_bf16_f32 v21, v22, v23
	v_cvt_pk_bf16_f32 v22, v24, v25
	v_cvt_pk_bf16_f32 v23, v26, v27
	s_nop 1
	v_permlane16_swap_b32_e32 v20, v22
	v_permlane16_swap_b32_e32 v21, v23
	global_store_dwordx4 v8, v[20:23], s[92:93]
	v_pk_mul_f32 v[28:29], v[4:5], v[28:29] op_sel_hi:[0,1]
	v_pk_mul_f32 v[30:31], v[4:5], v[30:31] op_sel_hi:[0,1]
	v_pk_mul_f32 v[32:33], v[4:5], v[32:33] op_sel_hi:[0,1]
	v_pk_mul_f32 v[34:35], v[4:5], v[34:35] op_sel_hi:[0,1]
	v_cvt_pk_bf16_f32 v28, v28, v29
	v_cvt_pk_bf16_f32 v29, v30, v31
	v_cvt_pk_bf16_f32 v30, v32, v33
	v_cvt_pk_bf16_f32 v31, v34, v35
	s_nop 1
	v_permlane16_swap_b32_e32 v28, v30
	v_permlane16_swap_b32_e32 v29, v31
	global_store_dwordx4 v8, v[28:31], s[92:93] offset:64
	v_pk_mul_f32 v[36:37], v[4:5], v[36:37] op_sel_hi:[0,1]
	v_pk_mul_f32 v[38:39], v[4:5], v[38:39] op_sel_hi:[0,1]
	v_pk_mul_f32 v[40:41], v[4:5], v[40:41] op_sel_hi:[0,1]
	v_pk_mul_f32 v[42:43], v[4:5], v[42:43] op_sel_hi:[0,1]
	v_cvt_pk_bf16_f32 v36, v36, v37
	v_cvt_pk_bf16_f32 v37, v38, v39
	v_cvt_pk_bf16_f32 v38, v40, v41
	v_cvt_pk_bf16_f32 v39, v42, v43
	s_nop 1
	v_permlane16_swap_b32_e32 v36, v38
	v_permlane16_swap_b32_e32 v37, v39
	global_store_dwordx4 v8, v[36:39], s[92:93] offset:128
	v_pk_mul_f32 v[44:45], v[4:5], v[44:45] op_sel_hi:[0,1]
	v_pk_mul_f32 v[46:47], v[4:5], v[46:47] op_sel_hi:[0,1]
	v_pk_mul_f32 v[0:1], v[4:5], v[0:1] op_sel_hi:[0,1]
	v_pk_mul_f32 v[2:3], v[4:5], v[2:3] op_sel_hi:[0,1]
	v_cvt_pk_bf16_f32 v44, v44, v45
	v_cvt_pk_bf16_f32 v45, v46, v47
	v_cvt_pk_bf16_f32 v46, v0, v1
	v_cvt_pk_bf16_f32 v47, v2, v3
	s_nop 1
	v_permlane16_swap_b32_e32 v44, v46
	v_permlane16_swap_b32_e32 v45, v47
	global_store_dwordx4 v8, v[44:47], s[92:93] offset:192
	s_waitcnt lgkmcnt(0)
	s_barrier
	s_waitcnt vmcnt(0)
	s_barrier
	s_mov_b64 s[0:1], exec
	v_readlane_b32 s8, v255, 50
	v_readlane_b32 s9, v255, 51
	s_and_b64 s[8:9], s[0:1], s[8:9]
	s_mov_b64 exec, s[8:9]
	s_cbranch_execz .LBB0_363
	v_mov_b32_e32 v0, 0xf149f2ca
	s_mov_b64 s[8:9], exec
	v_readlane_b32 s10, v255, 52
	v_readlane_b32 s11, v255, 53
	s_and_b64 s[10:11], s[8:9], s[10:11]
	s_mov_b64 exec, s[10:11]
	s_cbranch_execz .LBB0_362
	v_or_b32_e32 v186, s16, v212
	v_lshl_add_u64 v[0:1], v[186:187], 2, s[48:49]
	global_load_dword v0, v[0:1], off
	s_waitcnt vmcnt(0)
	v_mul_f32_e32 v0, 0x3fb8aa3b, v0
